# norm rows: sum-of-squares wave reduction via DPP/permlane swaps instead of six ds_bpermute round trips (same butterfly order, bit-identical)
# speedup vs baseline: 1.0077x; 1.0025x over previous
; __device__ __forceinline__ unsigned pk2(float lo, float hi) { unsigned r; asm("v_cvt_pk_bf16_f32 %0, %1, %2" : "=v"(r) : "v"(lo), "v"(hi)); return r; }
; __device__ __forceinline__ float wave_sum(float v) {
; #pragma unroll
;     for (int o = 1; o < 64; o <<= 1) v += __shfl_xor(v, o);
;     return v;
; __device__ __forceinline__ void norm_phase(const Params& P, LAS unsigned char* lds, int layer, int which, int nrows, int flags, int fprev, int fnext, const float* g2ovr, const float* xsrc, const float* gcp) {
;     ...
;             float ss = 0.f;
; #pragma unroll
;             for (int j = 0; j < 4; ++j) ss += (v[j][0] * v[j][0] + v[j][1] * v[j][1]) + (v[j][2] * v[j][2] + v[j][3] * v[j][3]);
;             const float rstd = rsqrtf(wave_sum(ss) * (1.f / D) + 1e-6f);
; #pragma unroll
;             for (int j = 0; j < 4; ++j) v[j] = v[j] * rstd * ga[j] + sh[j];
;             int orow = r;
;             if ((flags & 1) && r < SEQ) orow = 128 * (r & 127) + (r >> 7);
;             u32x2* o8 = (u32x2*)(hbuf + (size_t)orow * D) + lane;
; #pragma unroll
;             for (int j = 0; j < 4; ++j) { u32x2 o; o.x = pk2(v[j][0], v[j][1]); o.y = pk2(v[j][2], v[j][3]); o8[64 * j] = o; }
.LBB0_1240:
	s_waitcnt vmcnt(3)
	v_pk_mul_f32 v[70:71], v[64:65], v[64:65]
	v_pk_mul_f32 v[72:73], v[62:63], v[62:63]
	s_waitcnt vmcnt(2)
	v_pk_mul_f32 v[66:67], v[60:61], v[60:61]
	v_pk_mul_f32 v[68:69], v[58:59], v[58:59]
	v_pk_mov_b32 v[76:77], v[72:73], v[70:71] op_sel:[1,0]
	v_mov_b32_e32 v73, v71
	v_pk_add_f32 v[70:71], v[76:77], v[72:73]
	v_pk_mov_b32 v[72:73], v[68:69], v[66:67] op_sel:[1,0]
	v_mov_b32_e32 v69, v67
	v_pk_add_f32 v[66:67], v[72:73], v[68:69]
	s_waitcnt vmcnt(1)
	v_mul_f32_e32 v0, v54, v54
	v_pk_add_f32 v[70:71], v[70:71], v[70:71] op_sel_hi:[0,1]
	v_pk_add_f32 v[66:67], v[66:67], v[66:67] op_sel_hi:[0,1]
	v_pk_fma_f32 v[68:69], v[54:55], v[54:55], v[0:1] op_sel_hi:[1,1,0]
	v_mul_f32_e32 v0, v56, v56
	v_pk_fma_f32 v[72:73], v[56:57], v[56:57], v[0:1] op_sel_hi:[1,1,0]
	s_waitcnt vmcnt(0)
	v_mul_f32_e32 v70, v52, v52
	v_mul_f32_e32 v66, v53, v53
	v_and_b32_e32 v0, 64, v209
	v_mul_f32_e32 v68, v50, v50
	v_mul_f32_e32 v72, v51, v51
	v_pk_add_f32 v[66:67], v[70:71], v[66:67]
	v_add_u32_e32 v70, 64, v0
	v_xor_b32_e32 v0, 1, v209
	v_pk_add_f32 v[68:69], v[68:69], v[72:73]
	v_cmp_lt_i32_e32 vcc, v0, v70
	v_pk_add_f32 v[66:67], v[68:69], v[66:67]
	s_mov_b32 s2, 0x800000
	v_cndmask_b32_e32 v0, v209, v0, vcc
	v_add_f32_e32 v66, v66, v67
	v_lshlrev_b32_e32 v0, 2, v0
	s_nop 0
	v_add_f32_dpp v67, v66, v66 quad_perm:[1,0,3,2] row_mask:0xf bank_mask:0xf
	v_xor_b32_e32 v66, 2, v209
	v_cmp_lt_i32_e32 vcc, v66, v70
	s_nop 1
	v_cndmask_b32_e32 v66, v209, v66, vcc
	v_lshlrev_b32_e32 v66, 2, v66
	v_add_f32_dpp v68, v67, v67 quad_perm:[2,3,0,1] row_mask:0xf bank_mask:0xf
	v_xor_b32_e32 v67, 4, v209
	v_cmp_lt_i32_e32 vcc, v67, v70
	s_nop 1
	v_cndmask_b32_e32 v67, v209, v67, vcc
	v_lshlrev_b32_e32 v67, 2, v67
	v_add_f32_dpp v69, v68, v68 row_half_mirror row_mask:0xf bank_mask:0xf
	v_xor_b32_e32 v68, 8, v209
	v_cmp_lt_i32_e32 vcc, v68, v70
	s_nop 1
	v_cndmask_b32_e32 v68, v209, v68, vcc
	v_lshlrev_b32_e32 v68, 2, v68
	v_add_f32_dpp v71, v69, v69 row_mirror row_mask:0xf bank_mask:0xf
	v_xor_b32_e32 v69, 16, v209
	v_cmp_lt_i32_e32 vcc, v69, v70
	s_nop 1
	v_cndmask_b32_e32 v69, v209, v69, vcc
	v_lshlrev_b32_e32 v69, 2, v69
	v_mov_b32_e32 v160, v71
	v_mov_b32_e32 v161, v71
	s_nop 1
	v_permlane16_swap_b32_e32 v160, v161
	s_nop 1
	v_add_f32_e32 v71, v160, v161
	v_xor_b32_e32 v72, 32, v209
	v_cmp_lt_i32_e32 vcc, v72, v70
	s_nop 1
	v_cndmask_b32_e32 v70, v209, v72, vcc
	v_lshlrev_b32_e32 v70, 2, v70
	v_mov_b32_e32 v160, v71
	v_mov_b32_e32 v161, v71
	s_nop 1
	v_permlane32_swap_b32_e32 v160, v161
	s_nop 1
	v_add_f32_e32 v71, v160, v161
	v_fmamk_f32 v71, v71, 0x3a800000, v197
	v_mul_f32_e32 v72, 0x4b800000, v71
	v_cmp_gt_f32_e32 vcc, s2, v71
	s_nop 1
	v_cndmask_b32_e32 v71, v71, v72, vcc
	v_rsq_f32_e32 v71, v71
	s_nop 0
	v_mul_f32_e32 v72, 0x45800000, v71
	v_cndmask_b32_e32 v72, v71, v72, vcc
	v_pk_mul_f32 v[76:77], v[62:63], v[72:73] op_sel_hi:[1,0]
	v_pk_mul_f32 v[62:63], v[64:65], v[72:73] op_sel_hi:[1,0]
	v_pk_fma_f32 v[64:65], v[18:19], v[76:77], v[10:11]
	v_pk_mul_f32 v[76:77], v[58:59], v[72:73] op_sel_hi:[1,0]
	v_pk_mul_f32 v[58:59], v[60:61], v[72:73] op_sel_hi:[1,0]
	v_pk_fma_f32 v[60:61], v[22:23], v[76:77], v[6:7]
	v_pk_mul_f32 v[76:77], v[54:55], v[72:73] op_sel_hi:[1,0]
	v_pk_mul_f32 v[54:55], v[56:57], v[72:73] op_sel_hi:[1,0]
	v_pk_fma_f32 v[56:57], v[26:27], v[76:77], v[2:3]
	v_pk_mul_f32 v[76:77], v[50:51], v[72:73] op_sel_hi:[1,0]
	v_pk_mul_f32 v[50:51], v[52:53], v[72:73] op_sel_hi:[1,0]
	v_and_b32_e32 v71, 0x3f80, v135
	v_ashrrev_i32_e32 v72, 7, v136
	v_add_u32_e32 v71, v71, v72
	s_and_b64 vcc, s[70:71], s[4:5]
	v_cndmask_b32_e32 v72, v136, v71, vcc
	v_ashrrev_i32_e32 v73, 31, v72
	v_lshlrev_b64 v[72:73], 11, v[72:73]
	v_pk_fma_f32 v[62:63], v[20:21], v[62:63], v[12:13]
	v_pk_fma_f32 v[52:53], v[30:31], v[76:77], v[14:15]
	v_lshl_add_u64 v[72:73], v[112:113], 0, v[72:73]
	v_cvt_pk_bf16_f32 v76, v64, v65
	v_cvt_pk_bf16_f32 v77, v62, v63
	v_pk_fma_f32 v[58:59], v[24:25], v[58:59], v[8:9]
	global_store_dwordx2 v[72:73], v[76:77], off
	v_cvt_pk_bf16_f32 v76, v60, v61
	v_cvt_pk_bf16_f32 v77, v58, v59
	v_pk_fma_f32 v[54:55], v[28:29], v[54:55], v[4:5]
	v_pk_fma_f32 v[50:51], v[32:33], v[50:51], v[16:17]
	global_store_dwordx2 v[72:73], v[76:77], off offset:512
	v_cvt_pk_bf16_f32 v76, v56, v57
	v_cvt_pk_bf16_f32 v77, v54, v55
	s_andn2_b64 vcc, exec, s[40:41]
	global_store_dwordx2 v[72:73], v[76:77], off offset:1024
	v_cvt_pk_bf16_f32 v76, v52, v53
	v_cvt_pk_bf16_f32 v77, v50, v51
	global_store_dwordx2 v[72:73], v[76:77], off offset:1536
	s_cbranch_vccnz .LBB0_1200
; #define LAS __attribute__((address_space(3)))
; __device__ __forceinline__ void norm_phase(const Params& P, LAS unsigned char* lds, int layer, int which, int nrows, int flags, int fprev, int fnext, const float* g2ovr, const float* xsrc, const float* gcp) {
;     ...
;             if (flags & 2) {
;                 float lg[8];
; #pragma unroll
;                 for (int e = 0; e < 8; ++e) lg[e] = 0.f;
; #pragma unroll
;                 for (int j = 0; j < 4; ++j)
; #pragma unroll
;                     for (int e = 0; e < 4; ++e) { const LAS f32x4* rr = (const LAS f32x4*)(rt + ((j * 4 + e) * 64 + lane) * 12); const f32x4 r0 = rr[0], r1 = rr[1]; const float hv = v[j][e];
;                         lg[0] += hv * r0[0]; lg[1] += hv * r0[1]; lg[2] += hv * r0[2]; lg[3] += hv * r0[3]; lg[4] += hv * r1[0]; lg[5] += hv * r1[1]; lg[6] += hv * r1[2]; lg[7] += hv * r1[3]; }
; #pragma unroll
;                 for (int e = 0; e < 8; ++e) lg[e] = wave_sum(lg[e]);
	ds_read_b128 v[76:79], v134
	ds_read_b128 v[80:83], v134 offset:16
	ds_read_b128 v[84:87], v134 offset:3072
	ds_read_b128 v[90:93], v134 offset:6160
	ds_read_b128 v[122:125], v134 offset:15376
	s_waitcnt lgkmcnt(4)
	v_fma_f32 v71, v64, v78, 0
	v_fma_f32 v140, v64, v79, 0
	s_waitcnt lgkmcnt(3)
	v_fma_f32 v141, v64, v80, 0
	v_fma_f32 v142, v64, v81, 0
	ds_read_b128 v[78:81], v134 offset:3088
	s_waitcnt lgkmcnt(3)
	v_fmac_f32_e32 v71, v65, v86
	v_fmac_f32_e32 v140, v65, v87
	ds_read_b128 v[86:89], v134 offset:6144
	v_fma_f32 v143, v64, v82, 0
	v_fma_f32 v144, v64, v83, 0
	s_waitcnt lgkmcnt(1)
	v_fmac_f32_e32 v141, v65, v78
	v_fmac_f32_e32 v142, v65, v79
	v_fmac_f32_e32 v143, v65, v80
	v_fmac_f32_e32 v144, v65, v81
	ds_read_b128 v[78:81], v134 offset:9216
	s_waitcnt lgkmcnt(1)
	v_fmac_f32_e32 v71, v62, v88
	v_fmac_f32_e32 v140, v62, v89
	v_fmac_f32_e32 v141, v62, v90
	v_fmac_f32_e32 v142, v62, v91
	ds_read_b128 v[88:91], v134 offset:9232
	v_fmac_f32_e32 v143, v62, v92
	v_fmac_f32_e32 v144, v62, v93
	s_waitcnt lgkmcnt(1)
	v_fmac_f32_e32 v71, v63, v80
	v_fmac_f32_e32 v140, v63, v81
	ds_read_b128 v[80:83], v134 offset:12288
	s_waitcnt lgkmcnt(1)
	v_fmac_f32_e32 v141, v63, v88
	v_fmac_f32_e32 v142, v63, v89
	ds_read_b128 v[92:95], v134 offset:12304
	v_fmac_f32_e32 v143, v63, v90
	v_fmac_f32_e32 v144, v63, v91
	ds_read_b128 v[88:91], v134 offset:15360
	s_waitcnt lgkmcnt(2)
	v_fmac_f32_e32 v71, v60, v82
	v_fmac_f32_e32 v140, v60, v83
	s_waitcnt lgkmcnt(1)
	v_fmac_f32_e32 v141, v60, v92
	v_fmac_f32_e32 v142, v60, v93
	v_fmac_f32_e32 v143, v60, v94
	v_fmac_f32_e32 v144, v60, v95
	s_waitcnt lgkmcnt(0)
	v_fmac_f32_e32 v71, v61, v90
	v_fmac_f32_e32 v140, v61, v91
	ds_read_b128 v[90:93], v134 offset:18432
	v_fmac_f32_e32 v141, v61, v122
	v_fmac_f32_e32 v142, v61, v123
	ds_read_b128 v[94:97], v134 offset:18448
	v_fmac_f32_e32 v143, v61, v124
	v_fmac_f32_e32 v144, v61, v125
	ds_read_b128 v[122:125], v134 offset:21504
	s_waitcnt lgkmcnt(2)
	v_fmac_f32_e32 v71, v58, v92
	v_fmac_f32_e32 v140, v58, v93
	s_waitcnt lgkmcnt(1)
	v_fmac_f32_e32 v141, v58, v94
	v_fmac_f32_e32 v142, v58, v95
	ds_read_b128 v[92:95], v134 offset:21520
	s_waitcnt lgkmcnt(1)
	v_fmac_f32_e32 v71, v59, v124
	v_fmac_f32_e32 v140, v59, v125
	ds_read_b128 v[124:127], v134 offset:24576
	v_pk_fma_f32 v[72:73], v[64:65], v[76:77], 0 op_sel_hi:[0,1,0]
	v_pk_fma_f32 v[64:65], v[64:65], v[84:85], v[72:73] op_sel:[1,0,0]
	v_fmac_f32_e32 v143, v58, v96
	v_pk_fma_f32 v[64:65], v[62:63], v[86:87], v[64:65] op_sel_hi:[0,1,1]
	v_mov_b32_e32 v62, v63
	v_pk_fma_f32 v[62:63], v[62:63], v[78:79], v[64:65] op_sel_hi:[0,1,1]
	v_fmac_f32_e32 v144, v58, v97
	v_pk_fma_f32 v[62:63], v[60:61], v[80:81], v[62:63] op_sel_hi:[0,1,1]
	s_waitcnt lgkmcnt(1)
	v_fmac_f32_e32 v141, v59, v92
	v_fmac_f32_e32 v142, v59, v93
	ds_read_b128 v[136:139], v134 offset:24592
	v_fmac_f32_e32 v143, v59, v94
	v_fmac_f32_e32 v144, v59, v95
	s_waitcnt lgkmcnt(1)
	v_fmac_f32_e32 v71, v56, v126
	v_fmac_f32_e32 v140, v56, v127
	ds_read_b128 v[92:95], v134 offset:27648
	ds_read_b128 v[126:129], v134 offset:27664
	v_pk_fma_f32 v[60:61], v[60:61], v[88:89], v[62:63] op_sel:[1,0,0]
	ds_read_b128 v[62:65], v134 offset:30736
	v_pk_fma_f32 v[60:61], v[58:59], v[90:91], v[60:61] op_sel_hi:[0,1,1]
	v_mov_b32_e32 v58, v59
	v_pk_fma_f32 v[58:59], v[58:59], v[122:123], v[60:61] op_sel_hi:[0,1,1]
	v_pk_fma_f32 v[58:59], v[56:57], v[124:125], v[58:59] op_sel_hi:[0,1,1]
	s_waitcnt lgkmcnt(2)
	v_pk_fma_f32 v[72:73], v[56:57], v[92:93], v[58:59] op_sel:[1,0,0]
	ds_read_b128 v[58:61], v134 offset:30720
	v_fmac_f32_e32 v141, v56, v136
	v_fmac_f32_e32 v142, v56, v137
	v_fmac_f32_e32 v71, v57, v94
	v_fmac_f32_e32 v140, v57, v95
	s_waitcnt lgkmcnt(2)
	v_fmac_f32_e32 v141, v57, v126
	v_fmac_f32_e32 v142, v57, v127
	ds_read_b128 v[76:79], v134 offset:33792
	s_waitcnt lgkmcnt(1)
	v_fmac_f32_e32 v71, v54, v60
	v_fmac_f32_e32 v140, v54, v61
	v_fmac_f32_e32 v141, v54, v62
	v_fmac_f32_e32 v142, v54, v63
	ds_read_b128 v[60:63], v134 offset:33808
	v_fmac_f32_e32 v143, v56, v138
	v_fmac_f32_e32 v144, v56, v139
	v_fmac_f32_e32 v143, v57, v128
	v_fmac_f32_e32 v144, v57, v129
	v_fmac_f32_e32 v143, v54, v64
	v_fmac_f32_e32 v144, v54, v65
	s_waitcnt lgkmcnt(1)
	v_fmac_f32_e32 v71, v55, v78
	v_fmac_f32_e32 v140, v55, v79
	ds_read_b128 v[78:81], v134 offset:36864
	ds_read_b128 v[82:85], v134 offset:36880
	s_waitcnt lgkmcnt(2)
	v_fmac_f32_e32 v141, v55, v60
	v_fmac_f32_e32 v142, v55, v61
	v_fmac_f32_e32 v143, v55, v62
	v_fmac_f32_e32 v144, v55, v63
	ds_read_b128 v[60:63], v134 offset:39936
	s_waitcnt lgkmcnt(2)
	v_fmac_f32_e32 v71, v52, v80
	v_fmac_f32_e32 v140, v52, v81
	v_pk_fma_f32 v[56:57], v[54:55], v[58:59], v[72:73] op_sel_hi:[0,1,1]
	v_mov_b32_e32 v54, v55
	s_waitcnt lgkmcnt(1)
	v_fmac_f32_e32 v141, v52, v82
	v_fmac_f32_e32 v142, v52, v83
	ds_read_b128 v[80:83], v134 offset:39952
	v_fmac_f32_e32 v143, v52, v84
	v_fmac_f32_e32 v144, v52, v85
	s_waitcnt lgkmcnt(1)
	v_fmac_f32_e32 v71, v53, v62
	v_fmac_f32_e32 v140, v53, v63
	ds_read_b128 v[62:65], v134 offset:43008
	ds_read_b128 v[84:87], v134 offset:43024
	ds_read_b128 v[88:91], v134 offset:46080
	ds_read_b128 v[92:95], v134 offset:46096
	v_pk_fma_f32 v[54:55], v[54:55], v[76:77], v[56:57] op_sel_hi:[0,1,1]
	v_pk_fma_f32 v[54:55], v[52:53], v[78:79], v[54:55] op_sel_hi:[0,1,1]
	v_pk_fma_f32 v[54:55], v[52:53], v[60:61], v[54:55] op_sel:[1,0,0]
	v_mov_b32_e32 v52, v51
	s_waitcnt lgkmcnt(3)
	v_pk_fma_f32 v[54:55], v[50:51], v[62:63], v[54:55] op_sel_hi:[0,1,1]
	s_waitcnt lgkmcnt(1)
	v_pk_fma_f32 v[54:55], v[52:53], v[88:89], v[54:55] op_sel_hi:[0,1,1]
	ds_bpermute_b32 v56, v0, v54
	ds_bpermute_b32 v57, v0, v55
	v_fmac_f32_e32 v141, v53, v80
	v_fmac_f32_e32 v142, v53, v81
	v_fmac_f32_e32 v143, v53, v82
	v_fmac_f32_e32 v144, v53, v83
	s_waitcnt lgkmcnt(0)
; __device__ __forceinline__ void norm_phase(const Params& P, LAS unsigned char* lds, int layer, int which, int nrows, int flags, int fprev, int fnext, const float* g2ovr, const float* xsrc, const float* gcp) {
;     ...
;                 for (int e = 0; e < 8; ++e) lg[e] = wave_sum(lg[e]);
	v_pk_add_f32 v[52:53], v[54:55], v[56:57]
	ds_bpermute_b32 v54, v66, v52
	ds_bpermute_b32 v55, v66, v53
	v_fmac_f32_e32 v71, v50, v64
	v_fmac_f32_e32 v71, v51, v90
	v_fmac_f32_e32 v140, v50, v65
	v_fmac_f32_e32 v141, v50, v84
	s_waitcnt lgkmcnt(0)
	v_pk_add_f32 v[52:53], v[52:53], v[54:55]
	v_fmac_f32_e32 v142, v50, v85
	v_fmac_f32_e32 v143, v50, v86
	v_fmac_f32_e32 v144, v50, v87
	ds_bpermute_b32 v54, v67, v52
	ds_bpermute_b32 v55, v67, v53
	ds_bpermute_b32 v50, v0, v71
	v_fmac_f32_e32 v140, v51, v91
	v_fmac_f32_e32 v141, v51, v92
	v_fmac_f32_e32 v142, v51, v93
	s_waitcnt lgkmcnt(1)
	v_pk_add_f32 v[52:53], v[52:53], v[54:55]
	s_waitcnt lgkmcnt(0)
	v_add_f32_e32 v56, v71, v50
	ds_bpermute_b32 v54, v68, v52
	ds_bpermute_b32 v55, v68, v53
	ds_bpermute_b32 v57, v66, v56
	v_fmac_f32_e32 v143, v51, v94
	v_fmac_f32_e32 v144, v51, v95
	ds_bpermute_b32 v61, v0, v142
	s_waitcnt lgkmcnt(2)
	v_pk_add_f32 v[50:51], v[52:53], v[54:55]
	s_waitcnt lgkmcnt(1)
	v_add_f32_e32 v55, v56, v57
	ds_bpermute_b32 v52, v69, v50
	ds_bpermute_b32 v53, v69, v51
	ds_bpermute_b32 v54, v0, v140
	ds_bpermute_b32 v56, v67, v55
	ds_bpermute_b32 v57, v0, v141
	s_waitcnt lgkmcnt(5)
	v_add_f32_e32 v61, v142, v61
	s_waitcnt lgkmcnt(3)
	v_pk_add_f32 v[50:51], v[50:51], v[52:53]
	s_waitcnt lgkmcnt(2)
	v_add_f32_e32 v52, v140, v54
	s_waitcnt lgkmcnt(1)
	v_add_f32_e32 v54, v55, v56
	s_waitcnt lgkmcnt(0)
	v_add_f32_e32 v55, v141, v57
	ds_bpermute_b32 v53, v66, v52
	ds_bpermute_b32 v56, v66, v55
	ds_bpermute_b32 v57, v68, v54
	ds_bpermute_b32 v62, v66, v61
	s_waitcnt lgkmcnt(3)
	v_add_f32_e32 v53, v52, v53
	s_waitcnt lgkmcnt(2)
	v_add_f32_e32 v55, v55, v56
	ds_bpermute_b32 v58, v67, v53
	ds_bpermute_b32 v56, v67, v55
	s_waitcnt lgkmcnt(3)
	v_add_f32_e32 v54, v54, v57
	ds_bpermute_b32 v59, v69, v54
	s_waitcnt lgkmcnt(3)
	v_add_f32_e32 v61, v61, v62
	s_waitcnt lgkmcnt(2)
	v_add_f32_e32 v57, v53, v58
	s_waitcnt lgkmcnt(1)
	v_add_f32_e32 v55, v55, v56
	ds_bpermute_b32 v58, v68, v57
	ds_bpermute_b32 v56, v68, v55
	s_waitcnt lgkmcnt(2)
	v_add_f32_e32 v54, v54, v59
	ds_bpermute_b32 v62, v67, v61
	ds_bpermute_b32 v52, v70, v50
	s_waitcnt lgkmcnt(3)
	v_add_f32_e32 v57, v57, v58
	s_waitcnt lgkmcnt(2)
	v_add_f32_e32 v59, v55, v56
	ds_bpermute_b32 v58, v69, v57
	ds_bpermute_b32 v60, v69, v59
	s_waitcnt lgkmcnt(3)
	v_add_f32_e32 v61, v61, v62
	ds_bpermute_b32 v62, v68, v61
	ds_bpermute_b32 v53, v70, v51
	s_waitcnt lgkmcnt(3)
	v_add_f32_e32 v56, v57, v58
	s_waitcnt lgkmcnt(2)
	v_add_f32_e32 v58, v59, v60
	ds_bpermute_b32 v60, v0, v143
	ds_bpermute_b32 v0, v0, v144
	s_waitcnt lgkmcnt(3)
	v_add_f32_e32 v61, v61, v62
	ds_bpermute_b32 v62, v69, v61
	ds_bpermute_b32 v55, v70, v54
	s_waitcnt lgkmcnt(3)
	v_add_f32_e32 v60, v143, v60
	s_waitcnt lgkmcnt(2)
	v_add_f32_e32 v0, v144, v0
	ds_bpermute_b32 v63, v66, v60
	ds_bpermute_b32 v64, v66, v0
	ds_bpermute_b32 v57, v70, v56
	ds_bpermute_b32 v59, v70, v58
	s_waitcnt lgkmcnt(3)
	v_add_f32_e32 v60, v60, v63
	s_waitcnt lgkmcnt(2)
	v_add_f32_e32 v0, v0, v64
	ds_bpermute_b32 v63, v67, v60
	ds_bpermute_b32 v64, v67, v0
	s_waitcnt lgkmcnt(1)
	v_add_f32_e32 v60, v60, v63
	s_waitcnt lgkmcnt(0)
	v_add_f32_e32 v0, v0, v64
	ds_bpermute_b32 v63, v68, v60
	ds_bpermute_b32 v64, v68, v0
	s_waitcnt lgkmcnt(1)
	v_add_f32_e32 v63, v60, v63
	s_waitcnt lgkmcnt(0)
	v_add_f32_e32 v64, v0, v64
	ds_bpermute_b32 v65, v69, v63
	ds_bpermute_b32 v66, v69, v64
	v_add_f32_e32 v0, v61, v62
	ds_bpermute_b32 v60, v70, v0
	s_waitcnt lgkmcnt(2)
	v_add_f32_e32 v61, v63, v65
	s_waitcnt lgkmcnt(1)
	v_add_f32_e32 v63, v64, v66
	ds_bpermute_b32 v62, v70, v61
	ds_bpermute_b32 v64, v70, v63
	s_and_saveexec_b64 s[62:63], s[0:1]
	s_cbranch_execz .LBB0_1199
; __device__ __forceinline__ void norm_phase(const Params& P, LAS unsigned char* lds, int layer, int which, int nrows, int flags, int fprev, int fnext, const float* g2ovr, const float* xsrc, const float* gcp) {
;     ...
;                 int e0 = 0; float v0 = lg[0];
; #pragma unroll
;                 for (int e = 1; e < 8; ++e) if (lg[e] > v0) { v0 = lg[e]; e0 = e; }
;                 int e1 = -1; float v1 = -3.0e38f;
; #pragma unroll
;                 for (int e = 0; e < 8; ++e) if (e != e0 && lg[e] > v1) { v1 = lg[e]; e1 = e; }
;                 if (lane == 0) {
;                     const int rho = ((r - gw) / ngw) * NWAVE + wave;
;                     etab[2 * rho] = e0; etab[2 * rho + 1] = e1;
;                     const float ex = __expf(v1 - v0), w0 = 1.f / (1.f + ex);
;                     ((float2*)(ws + O_RW))[r] = make_float2(w0, ex * w0);
;                 }
	v_pk_add_f32 v[50:51], v[50:51], v[52:53]
	v_add_f32_e32 v54, v54, v55
	v_cmp_gt_f32_e32 vcc, v51, v50
	v_add_f32_e32 v56, v56, v57
	v_add_f32_e32 v58, v58, v59
	v_cndmask_b32_e32 v52, v50, v51, vcc
	v_cmp_gt_f32_e64 s[4:5], v54, v52
	s_waitcnt lgkmcnt(2)
	v_add_f32_e32 v0, v0, v60
	s_waitcnt lgkmcnt(1)
	v_add_f32_e32 v61, v61, v62
	v_cndmask_b32_e64 v52, v52, v54, s[4:5]
	v_cmp_gt_f32_e64 s[6:7], v56, v52
	s_waitcnt lgkmcnt(0)
	v_add_f32_e32 v63, v63, v64
	s_mov_b32 s2, 0xff61b1e6
	v_cndmask_b32_e64 v52, v52, v56, s[6:7]
	v_cmp_gt_f32_e64 s[8:9], v58, v52
	v_cmp_nlt_f32_e64 s[18:19], s2, v50
	v_mov_b32_e32 v53, 0xff61b1e6
	v_cndmask_b32_e64 v52, v52, v58, s[8:9]
	v_cmp_gt_f32_e64 s[12:13], v0, v52
	s_abs_i32 s3, s66
	s_ashr_i32 s2, s66, 31
	v_cndmask_b32_e64 v52, v52, v0, s[12:13]
	v_cmp_gt_f32_e64 s[14:15], v61, v52
	s_xor_b32 s2, s2, s75
	s_nop 0
	v_cndmask_b32_e64 v55, v52, v61, s[14:15]
	v_cndmask_b32_e64 v52, 0, 1, vcc
	v_cndmask_b32_e64 v52, v52, 2, s[4:5]
	v_cndmask_b32_e64 v52, v52, 3, s[6:7]
	v_cndmask_b32_e64 v52, v52, 4, s[8:9]
	v_cndmask_b32_e64 v52, v52, 5, s[12:13]
	v_cndmask_b32_e64 v52, v52, 6, s[14:15]
	v_cmp_ngt_f32_e32 vcc, v63, v55
	s_and_b64 s[20:21], s[14:15], vcc
	s_nop 0
	v_cndmask_b32_e32 v52, 7, v52, vcc
	v_cmp_eq_u32_e64 s[16:17], 0, v52
	s_or_b64 s[16:17], s[16:17], s[18:19]
	v_cmp_ne_u32_e64 s[14:15], 1, v52
	v_cndmask_b32_e64 v50, v50, v53, s[16:17]
	v_cmp_gt_f32_e64 s[18:19], v51, v50
	s_and_b64 s[14:15], s[14:15], s[18:19]
	v_cndmask_b32_e64 v50, v50, v51, s[14:15]
	v_cmp_ne_u32_e64 s[12:13], 2, v52
	v_cmp_gt_f32_e64 s[18:19], v54, v50
	s_and_b64 s[12:13], s[12:13], s[18:19]
	v_cndmask_b32_e64 v50, v50, v54, s[12:13]
	v_cmp_ne_u32_e64 s[8:9], 3, v52
	v_cmp_gt_f32_e64 s[18:19], v56, v50
	s_and_b64 s[8:9], s[8:9], s[18:19]
	v_cndmask_b32_e64 v50, v50, v56, s[8:9]
	v_cmp_ne_u32_e64 s[6:7], 4, v52
	v_cmp_gt_f32_e64 s[18:19], v58, v50
	s_and_b64 s[6:7], s[6:7], s[18:19]
	v_cndmask_b32_e64 v50, v50, v58, s[6:7]
	v_cmp_ne_u32_e64 s[4:5], 5, v52
	v_cmp_gt_f32_e64 s[18:19], v0, v50
	s_and_b64 s[4:5], s[4:5], s[18:19]
	v_cndmask_b32_e64 v0, v50, v0, s[4:5]
	v_cndmask_b32_e64 v50, 0, -1, s[16:17]
	v_cndmask_b32_e64 v50, v50, 1, s[14:15]
	v_cmp_ngt_f32_e64 s[18:19], v61, v0
	v_cndmask_b32_e64 v50, v50, 2, s[12:13]
	s_or_b64 s[18:19], s[20:21], s[18:19]
	v_cndmask_b32_e64 v50, v50, 3, s[8:9]
	v_cndmask_b32_e64 v0, v61, v0, s[18:19]
	v_cndmask_b32_e64 v50, v50, 4, s[6:7]
	v_cmp_gt_f32_e64 s[20:21], v63, v0
	v_cndmask_b32_e64 v50, v50, 5, s[4:5]
	s_and_b64 s[20:21], vcc, s[20:21]
	v_cndmask_b32_e64 v50, 6, v50, s[18:19]
	v_cndmask_b32_e64 v0, v0, v63, s[20:21]
	v_cndmask_b32_e64 v53, v50, 7, s[20:21]
	v_cndmask_b32_e32 v50, v63, v55, vcc
	s_mul_hi_u32 s4, s3, s67
	s_mul_i32 s5, s4, s30
	v_sub_f32_e32 v0, v0, v50
	s_sub_i32 s3, s3, s5
	v_mul_f32_e32 v0, 0x3fb8aa3b, v0
	s_add_i32 s5, s4, 1
	s_sub_i32 s6, s3, s30
	v_exp_f32_e32 v0, v0
	s_cmp_ge_u32 s3, s30
	s_cselect_b32 s4, s5, s4
	s_cselect_b32 s3, s6, s3
	s_add_i32 s5, s4, 1
	s_cmp_ge_u32 s3, s30
	v_add_f32_e32 v50, 1.0, v0
	s_cselect_b32 s3, s5, s4
	v_div_scale_f32 v51, s[4:5], v50, v50, 1.0
	v_rcp_f32_e32 v54, v51
	s_xor_b32 s3, s3, s2
	s_sub_i32 s2, s3, s2
	v_lshl_add_u32 v55, s2, 6, v101
	ds_write_b64 v55, v[52:53] offset:49152
	v_fma_f32 v52, -v51, v54, 1.0
	v_fmac_f32_e32 v54, v52, v54
	v_div_scale_f32 v52, vcc, 1.0, v50, 1.0
	v_mul_f32_e32 v53, v52, v54
	v_fma_f32 v55, -v51, v53, v52
	v_fmac_f32_e32 v53, v55, v54
	v_fma_f32 v51, -v51, v53, v52
	v_div_fmas_f32 v51, v51, v54, v53
	v_lshl_add_u64 v[52:53], s[28:29], 0, v[118:119]
	v_div_fixup_f32 v50, v51, v50, 1.0
	v_add_co_u32_e32 v52, vcc, 0x119000, v52
	v_mul_f32_e32 v51, v0, v50
	s_nop 0
	v_addc_co_u32_e32 v53, vcc, 0, v53, vcc
	global_store_dwordx2 v[52:53], v[50:51], off
	s_branch .LBB0_1199
